# all GEMM loops: every s_setprio removed (no priority toggling anywhere), on v062
# speedup vs baseline: 1.0026x; 1.0006x over previous
.LBB0_728:
	s_add_u32 s86, s38, s8
	s_addc_u32 s87, s39, s9
	s_add_u32 s86, s86, 0x158080
	s_addc_u32 s87, s87, 0
	s_add_u32 s16, s38, s8
	s_addc_u32 s17, s39, s9
	s_add_u32 s16, s16, 0x100
	s_addc_u32 s17, s17, 0
	s_add_u32 s34, s41, s8
	s_addc_u32 s64, s10, s9
	s_add_i32 s65, 0, 0x10000
	s_cmpk_eq_i32 s8, 0x2a00
	s_cselect_b32 s49, s53, s17
	s_cselect_b32 s48, s52, s16
	s_cselect_b32 s17, s61, s64
	s_cselect_b32 s16, s60, s34
	s_add_i32 s34, 0, 0x14000
	v_add_u32_e32 v150, s65, v234
	v_add_u32_e32 v166, s34, v234
	ds_read_b128 v[138:141], v150
	ds_read_b128 v[142:145], v150 offset:1024
	ds_read_b128 v[146:149], v150 offset:2048
	ds_read_b128 v[150:153], v150 offset:3072
	ds_read_b128 v[154:157], v166
	ds_read_b128 v[158:161], v166 offset:1024
	ds_read_b128 v[162:165], v166 offset:2048
	ds_read_b128 v[166:169], v166 offset:3072
	s_add_i32 m0, s67, 0xc000
	ds_read_b128 v[170:173], v238
	ds_read_b128 v[174:177], v238 offset:1024
	ds_read_b128 v[178:181], v238 offset:2048
	ds_read_b128 v[182:185], v238 offset:3072
	ds_read_b128 v[186:189], v238 offset:4096
	ds_read_b128 v[190:193], v238 offset:5120
	ds_read_b128 v[194:197], v238 offset:6144
	ds_read_b128 v[208:211], v238 offset:7168
	global_load_lds_dwordx4 v206, s[86:87]
	s_add_i32 m0, s67, 0xe000
	s_nop 0
	global_load_lds_dwordx4 v204, s[86:87]
	s_waitcnt vmcnt(8)
	s_waitcnt lgkmcnt(0)
	s_barrier
	s_waitcnt lgkmcnt(0)
	v_mfma_f32_16x16x32_bf16 v[6:9], v[138:141], v[170:173], v[6:9]
	v_mfma_f32_16x16x32_bf16 v[130:133], v[146:149], v[170:173], v[130:133]
	v_mfma_f32_16x16x32_bf16 v[126:129], v[138:141], v[178:181], v[126:129]
	v_mfma_f32_16x16x32_bf16 v[122:125], v[146:149], v[178:181], v[122:125]
	v_mfma_f32_16x16x32_bf16 v[118:121], v[138:141], v[186:189], v[118:121]
	v_mfma_f32_16x16x32_bf16 v[114:117], v[146:149], v[186:189], v[114:117]
	v_mfma_f32_16x16x32_bf16 v[110:113], v[138:141], v[194:197], v[110:113]
	v_mfma_f32_16x16x32_bf16 v[106:109], v[146:149], v[194:197], v[106:109]
	v_mfma_f32_16x16x32_bf16 v[6:9], v[142:145], v[174:177], v[6:9]
	v_mfma_f32_16x16x32_bf16 v[130:133], v[150:153], v[174:177], v[130:133]
	v_mfma_f32_16x16x32_bf16 v[126:129], v[142:145], v[182:185], v[126:129]
	v_mfma_f32_16x16x32_bf16 v[122:125], v[150:153], v[182:185], v[122:125]
	v_mfma_f32_16x16x32_bf16 v[118:121], v[142:145], v[190:193], v[118:121]
	v_mfma_f32_16x16x32_bf16 v[114:117], v[150:153], v[190:193], v[114:117]
	v_mfma_f32_16x16x32_bf16 v[110:113], v[142:145], v[208:211], v[110:113]
	v_mfma_f32_16x16x32_bf16 v[106:109], v[150:153], v[208:211], v[106:109]
	v_mfma_f32_16x16x32_bf16 v[102:105], v[154:157], v[170:173], v[102:105]
	v_mfma_f32_16x16x32_bf16 v[98:101], v[162:165], v[170:173], v[98:101]
	v_mfma_f32_16x16x32_bf16 v[94:97], v[154:157], v[178:181], v[94:97]
	v_mfma_f32_16x16x32_bf16 v[90:93], v[162:165], v[178:181], v[90:93]
	v_mfma_f32_16x16x32_bf16 v[86:89], v[154:157], v[186:189], v[86:89]
	v_mfma_f32_16x16x32_bf16 v[82:85], v[162:165], v[186:189], v[82:85]
	v_mfma_f32_16x16x32_bf16 v[78:81], v[154:157], v[194:197], v[78:81]
	v_mfma_f32_16x16x32_bf16 v[74:77], v[162:165], v[194:197], v[74:77]
	v_mfma_f32_16x16x32_bf16 v[102:105], v[158:161], v[174:177], v[102:105]
	v_mfma_f32_16x16x32_bf16 v[98:101], v[166:169], v[174:177], v[98:101]
	v_mfma_f32_16x16x32_bf16 v[94:97], v[158:161], v[182:185], v[94:97]
	v_mfma_f32_16x16x32_bf16 v[90:93], v[166:169], v[182:185], v[90:93]
	v_mfma_f32_16x16x32_bf16 v[86:89], v[158:161], v[190:193], v[86:89]
	v_mfma_f32_16x16x32_bf16 v[82:85], v[166:169], v[190:193], v[82:85]
	v_mfma_f32_16x16x32_bf16 v[78:81], v[158:161], v[208:211], v[78:81]
	v_mfma_f32_16x16x32_bf16 v[74:77], v[166:169], v[208:211], v[74:77]
	s_barrier
	s_add_i32 s64, s65, s66
	s_mov_b32 m0, s64
	ds_read_b128 v[170:173], v238 offset:16384
	ds_read_b128 v[174:177], v238 offset:17408
	ds_read_b128 v[178:181], v238 offset:18432
	ds_read_b128 v[182:185], v238 offset:19456
	ds_read_b128 v[186:189], v238 offset:20480
	ds_read_b128 v[190:193], v238 offset:21504
	ds_read_b128 v[194:197], v238 offset:22528
	ds_read_b128 v[208:211], v238 offset:23552
	global_load_lds_dwordx4 v0, s[16:17]
	s_add_i32 m0, s64, 0x2000
	s_add_u32 s64, s16, 0x158000
	s_addc_u32 s65, s17, 0
	s_add_i32 s34, s34, s66
	global_load_lds_dwordx4 v14, s[16:17]
	s_mov_b32 m0, s34
	s_add_u32 s98, s48, s96
	s_addc_u32 s99, s49, s97
	global_load_lds_dwordx4 v0, s[64:65]
	s_add_i32 m0, s34, 0x2000
	s_nop 0
	global_load_lds_dwordx4 v14, s[64:65]
	s_mov_b32 m0, s67
	s_nop 0
	global_load_lds_dwordx4 v0, s[48:49]
	s_mov_b32 m0, s68
	s_nop 0
	global_load_lds_dwordx4 v14, s[48:49]
	s_waitcnt vmcnt(8)
	s_waitcnt lgkmcnt(0)
	s_barrier
	s_waitcnt lgkmcnt(0)
	v_mfma_f32_16x16x32_bf16 v[70:73], v[138:141], v[170:173], v[70:73]
	v_mfma_f32_16x16x32_bf16 v[66:69], v[146:149], v[170:173], v[66:69]
	v_mfma_f32_16x16x32_bf16 v[62:65], v[138:141], v[178:181], v[62:65]
	v_mfma_f32_16x16x32_bf16 v[58:61], v[146:149], v[178:181], v[58:61]
	v_mfma_f32_16x16x32_bf16 v[54:57], v[138:141], v[186:189], v[54:57]
	v_mfma_f32_16x16x32_bf16 v[50:53], v[146:149], v[186:189], v[50:53]
	v_mfma_f32_16x16x32_bf16 v[46:49], v[138:141], v[194:197], v[46:49]
	v_mfma_f32_16x16x32_bf16 v[42:45], v[146:149], v[194:197], v[42:45]
	v_mfma_f32_16x16x32_bf16 v[70:73], v[142:145], v[174:177], v[70:73]
	v_mfma_f32_16x16x32_bf16 v[66:69], v[150:153], v[174:177], v[66:69]
	v_mfma_f32_16x16x32_bf16 v[62:65], v[142:145], v[182:185], v[62:65]
	v_mfma_f32_16x16x32_bf16 v[58:61], v[150:153], v[182:185], v[58:61]
	v_mfma_f32_16x16x32_bf16 v[54:57], v[142:145], v[190:193], v[54:57]
	v_mfma_f32_16x16x32_bf16 v[50:53], v[150:153], v[190:193], v[50:53]
	v_mfma_f32_16x16x32_bf16 v[46:49], v[142:145], v[208:211], v[46:49]
	v_mfma_f32_16x16x32_bf16 v[42:45], v[150:153], v[208:211], v[42:45]
	v_mfma_f32_16x16x32_bf16 v[38:41], v[154:157], v[170:173], v[38:41]
	v_mfma_f32_16x16x32_bf16 v[34:37], v[162:165], v[170:173], v[34:37]
	v_mfma_f32_16x16x32_bf16 v[30:33], v[154:157], v[178:181], v[30:33]
	v_mfma_f32_16x16x32_bf16 v[26:29], v[162:165], v[178:181], v[26:29]
	v_mfma_f32_16x16x32_bf16 v[22:25], v[154:157], v[186:189], v[22:25]
	v_mfma_f32_16x16x32_bf16 v[18:21], v[162:165], v[186:189], v[18:21]
	v_mfma_f32_16x16x32_bf16 v[10:13], v[154:157], v[194:197], v[10:13]
	v_mfma_f32_16x16x32_bf16 v[2:5], v[162:165], v[194:197], v[2:5]
	v_mfma_f32_16x16x32_bf16 v[38:41], v[158:161], v[174:177], v[38:41]
	v_mfma_f32_16x16x32_bf16 v[34:37], v[166:169], v[174:177], v[34:37]
	v_mfma_f32_16x16x32_bf16 v[30:33], v[158:161], v[182:185], v[30:33]
	v_mfma_f32_16x16x32_bf16 v[26:29], v[166:169], v[182:185], v[26:29]
	v_mfma_f32_16x16x32_bf16 v[22:25], v[158:161], v[190:193], v[22:25]
	v_mfma_f32_16x16x32_bf16 v[18:21], v[166:169], v[190:193], v[18:21]
	v_mfma_f32_16x16x32_bf16 v[10:13], v[158:161], v[208:211], v[10:13]
	v_mfma_f32_16x16x32_bf16 v[2:5], v[166:169], v[208:211], v[2:5]
	s_barrier
	s_add_i32 s34, 0, 0x18000
	s_add_i32 s64, 0, 0x1c000
	v_add_u32_e32 v150, s34, v234
	v_add_u32_e32 v166, s64, v234
	ds_read_b128 v[138:141], v150
	ds_read_b128 v[142:145], v150 offset:1024
	ds_read_b128 v[146:149], v150 offset:2048
	ds_read_b128 v[150:153], v150 offset:3072
	ds_read_b128 v[154:157], v166
	ds_read_b128 v[158:161], v166 offset:1024
	ds_read_b128 v[162:165], v166 offset:2048
	ds_read_b128 v[166:169], v166 offset:3072
	s_add_u32 s48, s48, 0x158000
	s_addc_u32 s49, s49, 0
	s_mov_b32 m0, s69
	ds_read_b128 v[170:173], v238 offset:32768
	ds_read_b128 v[174:177], v238 offset:33792
	ds_read_b128 v[178:181], v238 offset:34816
	ds_read_b128 v[182:185], v238 offset:35840
	ds_read_b128 v[186:189], v238 offset:36864
	ds_read_b128 v[190:193], v238 offset:37888
	ds_read_b128 v[194:197], v238 offset:38912
	ds_read_b128 v[208:211], v238 offset:39936
	global_load_lds_dwordx4 v0, s[48:49]
	s_mov_b32 m0, s70
	s_nop 0
	global_load_lds_dwordx4 v14, s[48:49]
	s_waitcnt vmcnt(8)
	s_waitcnt lgkmcnt(0)
	s_barrier
	s_waitcnt lgkmcnt(0)
	v_mfma_f32_16x16x32_bf16 v[6:9], v[138:141], v[170:173], v[6:9]
	v_mfma_f32_16x16x32_bf16 v[130:133], v[146:149], v[170:173], v[130:133]
	v_mfma_f32_16x16x32_bf16 v[126:129], v[138:141], v[178:181], v[126:129]
	v_mfma_f32_16x16x32_bf16 v[122:125], v[146:149], v[178:181], v[122:125]
	v_mfma_f32_16x16x32_bf16 v[118:121], v[138:141], v[186:189], v[118:121]
	v_mfma_f32_16x16x32_bf16 v[114:117], v[146:149], v[186:189], v[114:117]
	v_mfma_f32_16x16x32_bf16 v[110:113], v[138:141], v[194:197], v[110:113]
	v_mfma_f32_16x16x32_bf16 v[106:109], v[146:149], v[194:197], v[106:109]
	v_mfma_f32_16x16x32_bf16 v[6:9], v[142:145], v[174:177], v[6:9]
	v_mfma_f32_16x16x32_bf16 v[130:133], v[150:153], v[174:177], v[130:133]
	v_mfma_f32_16x16x32_bf16 v[126:129], v[142:145], v[182:185], v[126:129]
	v_mfma_f32_16x16x32_bf16 v[122:125], v[150:153], v[182:185], v[122:125]
	v_mfma_f32_16x16x32_bf16 v[118:121], v[142:145], v[190:193], v[118:121]
	v_mfma_f32_16x16x32_bf16 v[114:117], v[150:153], v[190:193], v[114:117]
	v_mfma_f32_16x16x32_bf16 v[110:113], v[142:145], v[208:211], v[110:113]
	v_mfma_f32_16x16x32_bf16 v[106:109], v[150:153], v[208:211], v[106:109]
	v_mfma_f32_16x16x32_bf16 v[102:105], v[154:157], v[170:173], v[102:105]
	v_mfma_f32_16x16x32_bf16 v[98:101], v[162:165], v[170:173], v[98:101]
	v_mfma_f32_16x16x32_bf16 v[94:97], v[154:157], v[178:181], v[94:97]
	v_mfma_f32_16x16x32_bf16 v[90:93], v[162:165], v[178:181], v[90:93]
	v_mfma_f32_16x16x32_bf16 v[86:89], v[154:157], v[186:189], v[86:89]
	v_mfma_f32_16x16x32_bf16 v[82:85], v[162:165], v[186:189], v[82:85]
	v_mfma_f32_16x16x32_bf16 v[78:81], v[154:157], v[194:197], v[78:81]
	v_mfma_f32_16x16x32_bf16 v[74:77], v[162:165], v[194:197], v[74:77]
	v_mfma_f32_16x16x32_bf16 v[102:105], v[158:161], v[174:177], v[102:105]
	v_mfma_f32_16x16x32_bf16 v[98:101], v[166:169], v[174:177], v[98:101]
	v_mfma_f32_16x16x32_bf16 v[94:97], v[158:161], v[182:185], v[94:97]
	v_mfma_f32_16x16x32_bf16 v[90:93], v[166:169], v[182:185], v[90:93]
	v_mfma_f32_16x16x32_bf16 v[86:89], v[158:161], v[190:193], v[86:89]
	v_mfma_f32_16x16x32_bf16 v[82:85], v[166:169], v[190:193], v[82:85]
	v_mfma_f32_16x16x32_bf16 v[78:81], v[158:161], v[208:211], v[78:81]
	v_mfma_f32_16x16x32_bf16 v[74:77], v[166:169], v[208:211], v[74:77]
	s_barrier
	s_add_i32 s34, s34, s66
	s_add_u32 s86, s16, s96
	s_addc_u32 s87, s17, s97
	s_mov_b32 m0, s34
	ds_read_b128 v[170:173], v238 offset:49152
	ds_read_b128 v[174:177], v238 offset:50176
	ds_read_b128 v[178:181], v238 offset:51200
	ds_read_b128 v[182:185], v238 offset:52224
	ds_read_b128 v[186:189], v238 offset:53248
	ds_read_b128 v[190:193], v238 offset:54272
	ds_read_b128 v[194:197], v238 offset:55296
	ds_read_b128 v[208:211], v238 offset:56320
	global_load_lds_dwordx4 v0, s[86:87]
	s_add_i32 m0, s34, 0x2000
	s_add_u32 s16, s16, 0x158080
	s_addc_u32 s17, s17, 0
	s_add_i32 s34, s64, s66
	global_load_lds_dwordx4 v14, s[86:87]
	s_mov_b32 m0, s34
	s_nop 0
	global_load_lds_dwordx4 v0, s[16:17]
	s_add_i32 m0, s34, 0x2000
	s_nop 0
	global_load_lds_dwordx4 v14, s[16:17]
	s_mov_b32 m0, s76
	s_nop 0
	global_load_lds_dwordx4 v0, s[98:99]
	s_mov_b32 m0, s77
	s_nop 0
	global_load_lds_dwordx4 v14, s[98:99]
	s_waitcnt vmcnt(8)
	s_waitcnt lgkmcnt(0)
	s_barrier
	s_waitcnt lgkmcnt(0)
	v_mfma_f32_16x16x32_bf16 v[70:73], v[138:141], v[170:173], v[70:73]
	v_mfma_f32_16x16x32_bf16 v[66:69], v[146:149], v[170:173], v[66:69]
	v_mfma_f32_16x16x32_bf16 v[62:65], v[138:141], v[178:181], v[62:65]
	v_mfma_f32_16x16x32_bf16 v[58:61], v[146:149], v[178:181], v[58:61]
	v_mfma_f32_16x16x32_bf16 v[54:57], v[138:141], v[186:189], v[54:57]
	v_mfma_f32_16x16x32_bf16 v[50:53], v[146:149], v[186:189], v[50:53]
	v_mfma_f32_16x16x32_bf16 v[46:49], v[138:141], v[194:197], v[46:49]
	v_mfma_f32_16x16x32_bf16 v[42:45], v[146:149], v[194:197], v[42:45]
	v_mfma_f32_16x16x32_bf16 v[70:73], v[142:145], v[174:177], v[70:73]
	v_mfma_f32_16x16x32_bf16 v[66:69], v[150:153], v[174:177], v[66:69]
	v_mfma_f32_16x16x32_bf16 v[62:65], v[142:145], v[182:185], v[62:65]
	v_mfma_f32_16x16x32_bf16 v[58:61], v[150:153], v[182:185], v[58:61]
	v_mfma_f32_16x16x32_bf16 v[54:57], v[142:145], v[190:193], v[54:57]
	v_mfma_f32_16x16x32_bf16 v[50:53], v[150:153], v[190:193], v[50:53]
	v_mfma_f32_16x16x32_bf16 v[46:49], v[142:145], v[208:211], v[46:49]
	v_mfma_f32_16x16x32_bf16 v[42:45], v[150:153], v[208:211], v[42:45]
	v_mfma_f32_16x16x32_bf16 v[38:41], v[154:157], v[170:173], v[38:41]
	v_mfma_f32_16x16x32_bf16 v[34:37], v[162:165], v[170:173], v[34:37]
	v_mfma_f32_16x16x32_bf16 v[30:33], v[154:157], v[178:181], v[30:33]
	v_mfma_f32_16x16x32_bf16 v[26:29], v[162:165], v[178:181], v[26:29]
	v_mfma_f32_16x16x32_bf16 v[22:25], v[154:157], v[186:189], v[22:25]
	v_mfma_f32_16x16x32_bf16 v[18:21], v[162:165], v[186:189], v[18:21]
	v_mfma_f32_16x16x32_bf16 v[10:13], v[154:157], v[194:197], v[10:13]
	v_mfma_f32_16x16x32_bf16 v[2:5], v[162:165], v[194:197], v[2:5]
	v_mfma_f32_16x16x32_bf16 v[38:41], v[158:161], v[174:177], v[38:41]
	v_mfma_f32_16x16x32_bf16 v[34:37], v[166:169], v[174:177], v[34:37]
	v_mfma_f32_16x16x32_bf16 v[30:33], v[158:161], v[182:185], v[30:33]
	v_mfma_f32_16x16x32_bf16 v[26:29], v[166:169], v[182:185], v[26:29]
	v_mfma_f32_16x16x32_bf16 v[22:25], v[158:161], v[190:193], v[22:25]
	v_mfma_f32_16x16x32_bf16 v[18:21], v[166:169], v[190:193], v[18:21]
	v_mfma_f32_16x16x32_bf16 v[10:13], v[158:161], v[208:211], v[10:13]
	v_mfma_f32_16x16x32_bf16 v[2:5], v[166:169], v[208:211], v[2:5]
	s_barrier
	s_add_i32 s11, s11, 2
	s_add_u32 s8, s8, 0x100
	s_addc_u32 s9, s9, 0
	s_cmpk_gt_u32 s11, 0x53
	s_cbranch_scc0 .LBB0_728
	s_and_b64 vcc, exec, s[28:29]
	s_cbranch_vccz .LBB0_731
	s_barrier

.LBB0_1045:
	s_add_u32 s46, s6, 0xfff80080
	s_addc_u32 s47, s7, -1
	s_add_i32 s52, 0, 0x10000
	s_cmp_eq_u32 s41, 28
	s_cselect_b32 s49, s9, s47
	s_cselect_b32 s48, s29, s46
	v_add_u32_e32 v0, s52, v149
	s_cselect_b32 s47, s31, s40
	s_cselect_b32 s46, s34, s39
	s_add_i32 s60, 0, 0x14000
	ds_read_b128 v[134:137], v0
	ds_read_b128 v[138:141], v0 offset:1024
	ds_read_b128 v[160:163], v0 offset:2048
	ds_read_b128 v[164:167], v0 offset:3072
	v_add_u32_e32 v0, s60, v149
	ds_read_b128 v[168:171], v0
	ds_read_b128 v[172:175], v0 offset:1024
	ds_read_b128 v[176:179], v0 offset:2048
	ds_read_b128 v[188:191], v0 offset:3072
	s_add_i32 m0, s63, 0xc000
	ds_read_b128 v[192:195], v186
	ds_read_b128 v[204:207], v186 offset:1024
	ds_read_b128 v[208:211], v186 offset:2048
	ds_read_b128 v[212:215], v186 offset:3072
	ds_read_b128 v[216:219], v186 offset:4096
	ds_read_b128 v[220:223], v186 offset:5120
	ds_read_b128 v[224:227], v186 offset:6144
	ds_read_b128 v[234:237], v186 offset:7168
	global_load_lds_dwordx4 v158, s[6:7]
	s_add_i32 m0, s63, 0xe000
	s_nop 0
	global_load_lds_dwordx4 v156, s[6:7]
	s_waitcnt vmcnt(8)
	s_waitcnt lgkmcnt(0)
	s_barrier
	s_waitcnt lgkmcnt(0)
	v_mfma_f32_16x16x32_bf16 v[130:133], v[134:137], v[192:195], v[130:133]
	v_mfma_f32_16x16x32_bf16 v[126:129], v[160:163], v[192:195], v[126:129]
	v_mfma_f32_16x16x32_bf16 v[114:117], v[134:137], v[208:211], v[114:117]
	v_mfma_f32_16x16x32_bf16 v[110:113], v[160:163], v[208:211], v[110:113]
	v_mfma_f32_16x16x32_bf16 v[98:101], v[134:137], v[216:219], v[98:101]
	v_mfma_f32_16x16x32_bf16 v[94:97], v[160:163], v[216:219], v[94:97]
	v_mfma_f32_16x16x32_bf16 v[82:85], v[134:137], v[224:227], v[82:85]
	v_mfma_f32_16x16x32_bf16 v[78:81], v[160:163], v[224:227], v[78:81]
	v_mfma_f32_16x16x32_bf16 v[130:133], v[138:141], v[204:207], v[130:133]
	v_mfma_f32_16x16x32_bf16 v[126:129], v[164:167], v[204:207], v[126:129]
	v_mfma_f32_16x16x32_bf16 v[114:117], v[138:141], v[212:215], v[114:117]
	v_mfma_f32_16x16x32_bf16 v[110:113], v[164:167], v[212:215], v[110:113]
	v_mfma_f32_16x16x32_bf16 v[98:101], v[138:141], v[220:223], v[98:101]
	v_mfma_f32_16x16x32_bf16 v[94:97], v[164:167], v[220:223], v[94:97]
	v_mfma_f32_16x16x32_bf16 v[82:85], v[138:141], v[234:237], v[82:85]
	v_mfma_f32_16x16x32_bf16 v[78:81], v[164:167], v[234:237], v[78:81]
	v_mfma_f32_16x16x32_bf16 v[122:125], v[168:171], v[192:195], v[122:125]
	v_mfma_f32_16x16x32_bf16 v[118:121], v[176:179], v[192:195], v[118:121]
	v_mfma_f32_16x16x32_bf16 v[106:109], v[168:171], v[208:211], v[106:109]
	v_mfma_f32_16x16x32_bf16 v[102:105], v[176:179], v[208:211], v[102:105]
	v_mfma_f32_16x16x32_bf16 v[90:93], v[168:171], v[216:219], v[90:93]
	v_mfma_f32_16x16x32_bf16 v[86:89], v[176:179], v[216:219], v[86:89]
	v_mfma_f32_16x16x32_bf16 v[74:77], v[168:171], v[224:227], v[74:77]
	v_mfma_f32_16x16x32_bf16 v[70:73], v[176:179], v[224:227], v[70:73]
	v_mfma_f32_16x16x32_bf16 v[122:125], v[172:175], v[204:207], v[122:125]
	v_mfma_f32_16x16x32_bf16 v[118:121], v[188:191], v[204:207], v[118:121]
	v_mfma_f32_16x16x32_bf16 v[106:109], v[172:175], v[212:215], v[106:109]
	v_mfma_f32_16x16x32_bf16 v[102:105], v[188:191], v[212:215], v[102:105]
	v_mfma_f32_16x16x32_bf16 v[90:93], v[172:175], v[220:223], v[90:93]
	v_mfma_f32_16x16x32_bf16 v[86:89], v[188:191], v[220:223], v[86:89]
	v_mfma_f32_16x16x32_bf16 v[74:77], v[172:175], v[234:237], v[74:77]
	v_mfma_f32_16x16x32_bf16 v[70:73], v[188:191], v[234:237], v[70:73]
	s_barrier
	s_add_i32 s52, s52, s56
	s_mov_b32 m0, s52
	ds_read_b128 v[192:195], v186 offset:16384
	ds_read_b128 v[204:207], v186 offset:17408
	ds_read_b128 v[208:211], v186 offset:18432
	ds_read_b128 v[212:215], v186 offset:19456
	ds_read_b128 v[216:219], v186 offset:20480
	ds_read_b128 v[220:223], v186 offset:21504
	ds_read_b128 v[224:227], v186 offset:22528
	ds_read_b128 v[234:237], v186 offset:23552
	global_load_lds_dwordx4 v142, s[46:47]
	s_add_i32 m0, s52, 0x2000
	s_add_u32 s52, s46, 0x80000
	s_addc_u32 s53, s47, 0
	s_add_i32 s60, s60, s56
	global_load_lds_dwordx4 v146, s[46:47]
	s_mov_b32 m0, s60
	s_add_u32 s98, s48, s96
	s_addc_u32 s99, s49, s97
	global_load_lds_dwordx4 v142, s[52:53]
	s_add_i32 m0, s60, 0x2000
	s_nop 0
	global_load_lds_dwordx4 v146, s[52:53]
	s_mov_b32 m0, s63
	s_nop 0
	global_load_lds_dwordx4 v14, s[48:49]
	s_mov_b32 m0, s66
	s_nop 0
	global_load_lds_dwordx4 v144, s[48:49]
	s_waitcnt vmcnt(8)
	s_waitcnt lgkmcnt(0)
	s_barrier
	s_waitcnt lgkmcnt(0)
	v_mfma_f32_16x16x32_bf16 v[66:69], v[134:137], v[192:195], v[66:69]
	v_mfma_f32_16x16x32_bf16 v[62:65], v[160:163], v[192:195], v[62:65]
	v_mfma_f32_16x16x32_bf16 v[50:53], v[134:137], v[208:211], v[50:53]
	v_mfma_f32_16x16x32_bf16 v[46:49], v[160:163], v[208:211], v[46:49]
	v_mfma_f32_16x16x32_bf16 v[34:37], v[134:137], v[216:219], v[34:37]
	v_mfma_f32_16x16x32_bf16 v[30:33], v[160:163], v[216:219], v[30:33]
	v_mfma_f32_16x16x32_bf16 v[18:21], v[134:137], v[224:227], v[18:21]
	v_mfma_f32_16x16x32_bf16 v[10:13], v[160:163], v[224:227], v[10:13]
	v_mfma_f32_16x16x32_bf16 v[66:69], v[138:141], v[204:207], v[66:69]
	v_mfma_f32_16x16x32_bf16 v[62:65], v[164:167], v[204:207], v[62:65]
	v_mfma_f32_16x16x32_bf16 v[50:53], v[138:141], v[212:215], v[50:53]
	v_mfma_f32_16x16x32_bf16 v[46:49], v[164:167], v[212:215], v[46:49]
	v_mfma_f32_16x16x32_bf16 v[34:37], v[138:141], v[220:223], v[34:37]
	v_mfma_f32_16x16x32_bf16 v[30:33], v[164:167], v[220:223], v[30:33]
	v_mfma_f32_16x16x32_bf16 v[18:21], v[138:141], v[234:237], v[18:21]
	v_mfma_f32_16x16x32_bf16 v[10:13], v[164:167], v[234:237], v[10:13]
	v_mfma_f32_16x16x32_bf16 v[58:61], v[168:171], v[192:195], v[58:61]
	v_mfma_f32_16x16x32_bf16 v[54:57], v[176:179], v[192:195], v[54:57]
	v_mfma_f32_16x16x32_bf16 v[42:45], v[168:171], v[208:211], v[42:45]
	v_mfma_f32_16x16x32_bf16 v[38:41], v[176:179], v[208:211], v[38:41]
	v_mfma_f32_16x16x32_bf16 v[26:29], v[168:171], v[216:219], v[26:29]
	v_mfma_f32_16x16x32_bf16 v[22:25], v[176:179], v[216:219], v[22:25]
	v_mfma_f32_16x16x32_bf16 v[6:9], v[168:171], v[224:227], v[6:9]
	v_mfma_f32_16x16x32_bf16 v[2:5], v[176:179], v[224:227], v[2:5]
	v_mfma_f32_16x16x32_bf16 v[58:61], v[172:175], v[204:207], v[58:61]
	v_mfma_f32_16x16x32_bf16 v[54:57], v[188:191], v[204:207], v[54:57]
	v_mfma_f32_16x16x32_bf16 v[42:45], v[172:175], v[212:215], v[42:45]
	v_mfma_f32_16x16x32_bf16 v[38:41], v[188:191], v[212:215], v[38:41]
	v_mfma_f32_16x16x32_bf16 v[26:29], v[172:175], v[220:223], v[26:29]
	v_mfma_f32_16x16x32_bf16 v[22:25], v[188:191], v[220:223], v[22:25]
	v_mfma_f32_16x16x32_bf16 v[6:9], v[172:175], v[234:237], v[6:9]
	v_mfma_f32_16x16x32_bf16 v[2:5], v[188:191], v[234:237], v[2:5]
	s_barrier
	s_add_i32 s52, 0, 0x18000
	v_add_u32_e32 v0, s52, v149
	s_add_i32 s53, 0, 0x1c000
	ds_read_b128 v[134:137], v0
	ds_read_b128 v[138:141], v0 offset:1024
	ds_read_b128 v[160:163], v0 offset:2048
	ds_read_b128 v[164:167], v0 offset:3072
	v_add_u32_e32 v0, s53, v149
	ds_read_b128 v[168:171], v0
	ds_read_b128 v[172:175], v0 offset:1024
	ds_read_b128 v[176:179], v0 offset:2048
	ds_read_b128 v[188:191], v0 offset:3072
	s_add_u32 s48, s48, 0x80000
	s_addc_u32 s49, s49, 0
	s_mov_b32 m0, s67
	ds_read_b128 v[192:195], v186 offset:32768
	ds_read_b128 v[204:207], v186 offset:33792
	ds_read_b128 v[208:211], v186 offset:34816
	ds_read_b128 v[212:215], v186 offset:35840
	ds_read_b128 v[216:219], v186 offset:36864
	ds_read_b128 v[220:223], v186 offset:37888
	ds_read_b128 v[224:227], v186 offset:38912
	ds_read_b128 v[234:237], v186 offset:39936
	global_load_lds_dwordx4 v14, s[48:49]
	s_mov_b32 m0, s68
	s_nop 0
	global_load_lds_dwordx4 v144, s[48:49]
	s_waitcnt vmcnt(8)
	s_waitcnt lgkmcnt(0)
	s_barrier
	s_waitcnt lgkmcnt(0)
	v_mfma_f32_16x16x32_bf16 v[130:133], v[134:137], v[192:195], v[130:133]
	v_mfma_f32_16x16x32_bf16 v[126:129], v[160:163], v[192:195], v[126:129]
	v_mfma_f32_16x16x32_bf16 v[114:117], v[134:137], v[208:211], v[114:117]
	v_mfma_f32_16x16x32_bf16 v[110:113], v[160:163], v[208:211], v[110:113]
	v_mfma_f32_16x16x32_bf16 v[98:101], v[134:137], v[216:219], v[98:101]
	v_mfma_f32_16x16x32_bf16 v[94:97], v[160:163], v[216:219], v[94:97]
	v_mfma_f32_16x16x32_bf16 v[82:85], v[134:137], v[224:227], v[82:85]
	v_mfma_f32_16x16x32_bf16 v[78:81], v[160:163], v[224:227], v[78:81]
	v_mfma_f32_16x16x32_bf16 v[130:133], v[138:141], v[204:207], v[130:133]
	v_mfma_f32_16x16x32_bf16 v[126:129], v[164:167], v[204:207], v[126:129]
	v_mfma_f32_16x16x32_bf16 v[114:117], v[138:141], v[212:215], v[114:117]
	v_mfma_f32_16x16x32_bf16 v[110:113], v[164:167], v[212:215], v[110:113]
	v_mfma_f32_16x16x32_bf16 v[98:101], v[138:141], v[220:223], v[98:101]
	v_mfma_f32_16x16x32_bf16 v[94:97], v[164:167], v[220:223], v[94:97]
	v_mfma_f32_16x16x32_bf16 v[82:85], v[138:141], v[234:237], v[82:85]
	v_mfma_f32_16x16x32_bf16 v[78:81], v[164:167], v[234:237], v[78:81]
	v_mfma_f32_16x16x32_bf16 v[122:125], v[168:171], v[192:195], v[122:125]
	v_mfma_f32_16x16x32_bf16 v[118:121], v[176:179], v[192:195], v[118:121]
	v_mfma_f32_16x16x32_bf16 v[106:109], v[168:171], v[208:211], v[106:109]
	v_mfma_f32_16x16x32_bf16 v[102:105], v[176:179], v[208:211], v[102:105]
	v_mfma_f32_16x16x32_bf16 v[90:93], v[168:171], v[216:219], v[90:93]
	v_mfma_f32_16x16x32_bf16 v[86:89], v[176:179], v[216:219], v[86:89]
	v_mfma_f32_16x16x32_bf16 v[74:77], v[168:171], v[224:227], v[74:77]
	v_mfma_f32_16x16x32_bf16 v[70:73], v[176:179], v[224:227], v[70:73]
	v_mfma_f32_16x16x32_bf16 v[122:125], v[172:175], v[204:207], v[122:125]
	v_mfma_f32_16x16x32_bf16 v[118:121], v[188:191], v[204:207], v[118:121]
	v_mfma_f32_16x16x32_bf16 v[106:109], v[172:175], v[212:215], v[106:109]
	v_mfma_f32_16x16x32_bf16 v[102:105], v[188:191], v[212:215], v[102:105]
	v_mfma_f32_16x16x32_bf16 v[90:93], v[172:175], v[220:223], v[90:93]
	v_mfma_f32_16x16x32_bf16 v[86:89], v[188:191], v[220:223], v[86:89]
	v_mfma_f32_16x16x32_bf16 v[74:77], v[172:175], v[234:237], v[74:77]
	v_mfma_f32_16x16x32_bf16 v[70:73], v[188:191], v[234:237], v[70:73]
	s_barrier
	s_add_i32 s48, s52, s56
	s_add_u32 s88, s46, s96
	s_addc_u32 s89, s47, s97
	s_mov_b32 m0, s48
	ds_read_b128 v[192:195], v186 offset:49152
	ds_read_b128 v[204:207], v186 offset:50176
	ds_read_b128 v[208:211], v186 offset:51200
	ds_read_b128 v[212:215], v186 offset:52224
	ds_read_b128 v[216:219], v186 offset:53248
	ds_read_b128 v[220:223], v186 offset:54272
	ds_read_b128 v[224:227], v186 offset:55296
	ds_read_b128 v[234:237], v186 offset:56320
	global_load_lds_dwordx4 v142, s[88:89]
	s_add_i32 m0, s48, 0x2000
	s_add_u32 s46, s46, 0x80080
	s_addc_u32 s47, s47, 0
	s_add_i32 s48, s53, s56
	global_load_lds_dwordx4 v146, s[88:89]
	s_mov_b32 m0, s48
	s_nop 0
	global_load_lds_dwordx4 v142, s[46:47]
	s_add_i32 m0, s48, 0x2000
	s_nop 0
	global_load_lds_dwordx4 v146, s[46:47]
	s_mov_b32 m0, s78
	s_nop 0
	global_load_lds_dwordx4 v14, s[98:99]
	s_mov_b32 m0, s79
	s_nop 0
	global_load_lds_dwordx4 v144, s[98:99]
	s_waitcnt vmcnt(8)
	s_waitcnt lgkmcnt(0)
	s_barrier
	s_waitcnt lgkmcnt(0)
	v_mfma_f32_16x16x32_bf16 v[66:69], v[134:137], v[192:195], v[66:69]
	v_mfma_f32_16x16x32_bf16 v[62:65], v[160:163], v[192:195], v[62:65]
	v_mfma_f32_16x16x32_bf16 v[50:53], v[134:137], v[208:211], v[50:53]
	v_mfma_f32_16x16x32_bf16 v[46:49], v[160:163], v[208:211], v[46:49]
	v_mfma_f32_16x16x32_bf16 v[34:37], v[134:137], v[216:219], v[34:37]
	v_mfma_f32_16x16x32_bf16 v[30:33], v[160:163], v[216:219], v[30:33]
	v_mfma_f32_16x16x32_bf16 v[18:21], v[134:137], v[224:227], v[18:21]
	v_mfma_f32_16x16x32_bf16 v[10:13], v[160:163], v[224:227], v[10:13]
	v_mfma_f32_16x16x32_bf16 v[66:69], v[138:141], v[204:207], v[66:69]
	v_mfma_f32_16x16x32_bf16 v[62:65], v[164:167], v[204:207], v[62:65]
	v_mfma_f32_16x16x32_bf16 v[50:53], v[138:141], v[212:215], v[50:53]
	v_mfma_f32_16x16x32_bf16 v[46:49], v[164:167], v[212:215], v[46:49]
	v_mfma_f32_16x16x32_bf16 v[34:37], v[138:141], v[220:223], v[34:37]
	v_mfma_f32_16x16x32_bf16 v[30:33], v[164:167], v[220:223], v[30:33]
	v_mfma_f32_16x16x32_bf16 v[18:21], v[138:141], v[234:237], v[18:21]
	v_mfma_f32_16x16x32_bf16 v[10:13], v[164:167], v[234:237], v[10:13]
	v_mfma_f32_16x16x32_bf16 v[58:61], v[168:171], v[192:195], v[58:61]
	v_mfma_f32_16x16x32_bf16 v[54:57], v[176:179], v[192:195], v[54:57]
	v_mfma_f32_16x16x32_bf16 v[42:45], v[168:171], v[208:211], v[42:45]
	v_mfma_f32_16x16x32_bf16 v[38:41], v[176:179], v[208:211], v[38:41]
	v_mfma_f32_16x16x32_bf16 v[26:29], v[168:171], v[216:219], v[26:29]
	v_mfma_f32_16x16x32_bf16 v[22:25], v[176:179], v[216:219], v[22:25]
	v_mfma_f32_16x16x32_bf16 v[6:9], v[168:171], v[224:227], v[6:9]
	v_mfma_f32_16x16x32_bf16 v[2:5], v[176:179], v[224:227], v[2:5]
	v_mfma_f32_16x16x32_bf16 v[58:61], v[172:175], v[204:207], v[58:61]
	v_mfma_f32_16x16x32_bf16 v[54:57], v[188:191], v[204:207], v[54:57]
	v_mfma_f32_16x16x32_bf16 v[42:45], v[172:175], v[212:215], v[42:45]
	v_mfma_f32_16x16x32_bf16 v[38:41], v[188:191], v[212:215], v[38:41]
	v_mfma_f32_16x16x32_bf16 v[26:29], v[172:175], v[220:223], v[26:29]
	v_mfma_f32_16x16x32_bf16 v[22:25], v[188:191], v[220:223], v[22:25]
	v_mfma_f32_16x16x32_bf16 v[6:9], v[172:175], v[234:237], v[6:9]
	v_mfma_f32_16x16x32_bf16 v[2:5], v[188:191], v[234:237], v[2:5]
	s_barrier
	s_add_i32 s41, s41, 2
	s_add_u32 s39, s39, 0x100
	s_addc_u32 s40, s40, 0
	s_add_u32 s6, s6, 0x100
	s_addc_u32 s7, s7, 0
	s_cmp_gt_u32 s41, 29
	s_cbranch_scc0 .LBB0_1045
	s_and_b64 vcc, exec, s[22:23]
	s_cbranch_vccz .LBB0_1048
	s_barrier

.LBB0_1300:
	s_add_u32 s12, s41, s10
	s_addc_u32 s13, s44, s11
	s_add_u32 s12, s12, 0x40601100
	s_addc_u32 s13, s13, 0
	s_add_u32 s46, s39, s10
	s_addc_u32 s47, s40, s11
	s_add_i32 s48, 0, 0x10000
	v_add_u32_e32 v96, s48, v82
	ds_read_b128 v[84:87], v96
	ds_read_b128 v[88:91], v96 offset:1024
	ds_read_b128 v[92:95], v96 offset:2048
	ds_read_b128 v[96:99], v96 offset:3072
	s_cmpk_eq_i32 s10, 0x1f00
	s_cselect_b32 s15, s5, s13
	s_cselect_b32 s14, s4, s12
	s_cselect_b32 s13, s3, s47
	s_cselect_b32 s12, s2, s46
	v_lshl_add_u64 v[132:133], v[78:79], 0, s[10:11]
	s_add_i32 m0, s25, 0xc000
	ds_read_b128 v[100:103], v83
	ds_read_b128 v[104:107], v83 offset:1024
	ds_read_b128 v[108:111], v83 offset:2048
	ds_read_b128 v[112:115], v83 offset:3072
	ds_read_b128 v[116:119], v83 offset:4096
	ds_read_b128 v[120:123], v83 offset:5120
	ds_read_b128 v[124:127], v83 offset:6144
	ds_read_b128 v[128:131], v83 offset:7168
	global_load_lds_dwordx4 v[132:133], off
	v_lshl_add_u64 v[132:133], v[36:37], 0, s[10:11]
	s_add_i32 m0, s25, 0xe000
	s_nop 0
	global_load_lds_dwordx4 v[132:133], off
	s_waitcnt vmcnt(8)
	s_waitcnt lgkmcnt(0)
	s_barrier
	s_waitcnt lgkmcnt(0)
	v_mfma_f32_16x16x32_bf16 v[74:77], v[84:87], v[100:103], v[74:77]
	v_mfma_f32_16x16x32_bf16 v[70:73], v[92:95], v[100:103], v[70:73]
	v_mfma_f32_16x16x32_bf16 v[66:69], v[84:87], v[108:111], v[66:69]
	v_mfma_f32_16x16x32_bf16 v[62:65], v[92:95], v[108:111], v[62:65]
	v_mfma_f32_16x16x32_bf16 v[58:61], v[84:87], v[116:119], v[58:61]
	v_mfma_f32_16x16x32_bf16 v[54:57], v[92:95], v[116:119], v[54:57]
	v_mfma_f32_16x16x32_bf16 v[50:53], v[84:87], v[124:127], v[50:53]
	v_mfma_f32_16x16x32_bf16 v[46:49], v[92:95], v[124:127], v[46:49]
	v_mfma_f32_16x16x32_bf16 v[74:77], v[88:91], v[104:107], v[74:77]
	v_mfma_f32_16x16x32_bf16 v[70:73], v[96:99], v[104:107], v[70:73]
	v_mfma_f32_16x16x32_bf16 v[66:69], v[88:91], v[112:115], v[66:69]
	v_mfma_f32_16x16x32_bf16 v[62:65], v[96:99], v[112:115], v[62:65]
	v_mfma_f32_16x16x32_bf16 v[58:61], v[88:91], v[120:123], v[58:61]
	v_mfma_f32_16x16x32_bf16 v[54:57], v[96:99], v[120:123], v[54:57]
	v_mfma_f32_16x16x32_bf16 v[50:53], v[88:91], v[128:131], v[50:53]
	v_mfma_f32_16x16x32_bf16 v[46:49], v[96:99], v[128:131], v[46:49]
	s_barrier
	s_add_i32 s46, s48, s24
	v_lshl_add_u64 v[132:133], s[12:13], 0, v[0:1]
	s_mov_b32 m0, s46
	ds_read_b128 v[100:103], v83 offset:16384
	ds_read_b128 v[104:107], v83 offset:17408
	ds_read_b128 v[108:111], v83 offset:18432
	ds_read_b128 v[112:115], v83 offset:19456
	ds_read_b128 v[116:119], v83 offset:20480
	ds_read_b128 v[120:123], v83 offset:21504
	ds_read_b128 v[124:127], v83 offset:22528
	ds_read_b128 v[128:131], v83 offset:23552
	global_load_lds_dwordx4 v[132:133], off
	s_add_i32 m0, s46, 0x2000
	s_add_u32 s46, s12, 0x100000
	v_lshl_add_u64 v[134:135], s[12:13], 0, v[34:35]
	s_addc_u32 s47, s13, 0
	global_load_lds_dwordx4 v[134:135], off
	v_lshl_add_u64 v[136:137], s[46:47], 0, v[0:1]
	s_mov_b32 m0, s26
	v_lshl_add_u64 v[138:139], s[14:15], 0, v[32:33]
	global_load_lds_dwordx4 v[136:137], off
	v_lshl_add_u64 v[136:137], s[46:47], 0, v[34:35]
	s_mov_b32 m0, s27
	s_nop 0
	global_load_lds_dwordx4 v[136:137], off
	v_lshl_add_u64 v[136:137], s[14:15], 0, v[30:31]
	s_mov_b32 m0, s25
	s_nop 0
	global_load_lds_dwordx4 v[136:137], off
	s_mov_b32 m0, s28
	s_nop 0
	global_load_lds_dwordx4 v[138:139], off
	s_waitcnt vmcnt(8)
	s_waitcnt lgkmcnt(0)
	s_barrier
	s_waitcnt lgkmcnt(0)
	v_mfma_f32_16x16x32_bf16 v[42:45], v[84:87], v[100:103], v[42:45]
	v_mfma_f32_16x16x32_bf16 v[38:41], v[92:95], v[100:103], v[38:41]
	v_mfma_f32_16x16x32_bf16 v[26:29], v[84:87], v[108:111], v[26:29]
	v_mfma_f32_16x16x32_bf16 v[22:25], v[92:95], v[108:111], v[22:25]
	v_mfma_f32_16x16x32_bf16 v[18:21], v[84:87], v[116:119], v[18:21]
	v_mfma_f32_16x16x32_bf16 v[10:13], v[92:95], v[116:119], v[10:13]
	v_mfma_f32_16x16x32_bf16 v[6:9], v[84:87], v[124:127], v[6:9]
	v_mfma_f32_16x16x32_bf16 v[2:5], v[92:95], v[124:127], v[2:5]
	v_mfma_f32_16x16x32_bf16 v[42:45], v[88:91], v[104:107], v[42:45]
	v_mfma_f32_16x16x32_bf16 v[38:41], v[96:99], v[104:107], v[38:41]
	v_mfma_f32_16x16x32_bf16 v[26:29], v[88:91], v[112:115], v[26:29]
	v_mfma_f32_16x16x32_bf16 v[22:25], v[96:99], v[112:115], v[22:25]
	v_mfma_f32_16x16x32_bf16 v[18:21], v[88:91], v[120:123], v[18:21]
	v_mfma_f32_16x16x32_bf16 v[10:13], v[96:99], v[120:123], v[10:13]
	v_mfma_f32_16x16x32_bf16 v[6:9], v[88:91], v[128:131], v[6:9]
	v_mfma_f32_16x16x32_bf16 v[2:5], v[96:99], v[128:131], v[2:5]
	s_barrier
	s_add_i32 s46, 0, 0x18000
	v_add_u32_e32 v96, s46, v82
	ds_read_b128 v[84:87], v96
	ds_read_b128 v[88:91], v96 offset:1024
	ds_read_b128 v[92:95], v96 offset:2048
	ds_read_b128 v[96:99], v96 offset:3072
	s_add_u32 s14, s14, 0x80000
	s_addc_u32 s15, s15, 0
	s_mov_b32 m0, s29
	v_lshl_add_u64 v[140:141], s[14:15], 0, v[30:31]
	ds_read_b128 v[100:103], v83 offset:32768
	ds_read_b128 v[104:107], v83 offset:33792
	ds_read_b128 v[108:111], v83 offset:34816
	ds_read_b128 v[112:115], v83 offset:35840
	ds_read_b128 v[116:119], v83 offset:36864
	ds_read_b128 v[120:123], v83 offset:37888
	ds_read_b128 v[124:127], v83 offset:38912
	ds_read_b128 v[128:131], v83 offset:39936
	global_load_lds_dwordx4 v[140:141], off
	v_lshl_add_u64 v[140:141], s[14:15], 0, v[32:33]
	s_mov_b32 m0, s30
	s_nop 0
	global_load_lds_dwordx4 v[140:141], off
	s_waitcnt vmcnt(8)
	s_waitcnt lgkmcnt(0)
	s_barrier
	s_waitcnt lgkmcnt(0)
	v_mfma_f32_16x16x32_bf16 v[74:77], v[84:87], v[100:103], v[74:77]
	v_mfma_f32_16x16x32_bf16 v[70:73], v[92:95], v[100:103], v[70:73]
	v_mfma_f32_16x16x32_bf16 v[66:69], v[84:87], v[108:111], v[66:69]
	v_mfma_f32_16x16x32_bf16 v[62:65], v[92:95], v[108:111], v[62:65]
	v_mfma_f32_16x16x32_bf16 v[58:61], v[84:87], v[116:119], v[58:61]
	v_mfma_f32_16x16x32_bf16 v[54:57], v[92:95], v[116:119], v[54:57]
	v_mfma_f32_16x16x32_bf16 v[50:53], v[84:87], v[124:127], v[50:53]
	v_mfma_f32_16x16x32_bf16 v[46:49], v[92:95], v[124:127], v[46:49]
	v_mfma_f32_16x16x32_bf16 v[74:77], v[88:91], v[104:107], v[74:77]
	v_mfma_f32_16x16x32_bf16 v[70:73], v[96:99], v[104:107], v[70:73]
	v_mfma_f32_16x16x32_bf16 v[66:69], v[88:91], v[112:115], v[66:69]
	v_mfma_f32_16x16x32_bf16 v[62:65], v[96:99], v[112:115], v[62:65]
	v_mfma_f32_16x16x32_bf16 v[58:61], v[88:91], v[120:123], v[58:61]
	v_mfma_f32_16x16x32_bf16 v[54:57], v[96:99], v[120:123], v[54:57]
	v_mfma_f32_16x16x32_bf16 v[50:53], v[88:91], v[128:131], v[50:53]
	v_mfma_f32_16x16x32_bf16 v[46:49], v[96:99], v[128:131], v[46:49]
	s_barrier
	s_add_i32 s14, s46, s24
	v_lshl_add_u64 v[132:133], v[132:133], 0, s[96:97]
	s_mov_b32 m0, s14
	ds_read_b128 v[100:103], v83 offset:49152
	ds_read_b128 v[104:107], v83 offset:50176
	ds_read_b128 v[108:111], v83 offset:51200
	ds_read_b128 v[112:115], v83 offset:52224
	ds_read_b128 v[116:119], v83 offset:53248
	ds_read_b128 v[120:123], v83 offset:54272
	ds_read_b128 v[124:127], v83 offset:55296
	ds_read_b128 v[128:131], v83 offset:56320
	global_load_lds_dwordx4 v[132:133], off
	s_add_i32 m0, s14, 0x2000
	s_add_u32 s12, s12, 0x100080
	v_lshl_add_u64 v[132:133], v[134:135], 0, s[96:97]
	s_addc_u32 s13, s13, 0
	global_load_lds_dwordx4 v[132:133], off
	v_lshl_add_u64 v[132:133], s[12:13], 0, v[0:1]
	s_mov_b32 m0, s37
	s_nop 0
	global_load_lds_dwordx4 v[132:133], off
	v_lshl_add_u64 v[132:133], s[12:13], 0, v[34:35]
	s_mov_b32 m0, s38
	s_nop 0
	global_load_lds_dwordx4 v[132:133], off
	v_lshl_add_u64 v[132:133], v[136:137], 0, s[96:97]
	s_mov_b32 m0, s34
	s_nop 0
	global_load_lds_dwordx4 v[132:133], off
	v_lshl_add_u64 v[132:133], v[138:139], 0, s[96:97]
	s_mov_b32 m0, s36
	s_nop 0
	global_load_lds_dwordx4 v[132:133], off
	s_waitcnt vmcnt(8)
	s_waitcnt lgkmcnt(0)
	s_barrier
	s_waitcnt lgkmcnt(0)
	v_mfma_f32_16x16x32_bf16 v[42:45], v[84:87], v[100:103], v[42:45]
	v_mfma_f32_16x16x32_bf16 v[38:41], v[92:95], v[100:103], v[38:41]
	v_mfma_f32_16x16x32_bf16 v[26:29], v[84:87], v[108:111], v[26:29]
	v_mfma_f32_16x16x32_bf16 v[22:25], v[92:95], v[108:111], v[22:25]
	v_mfma_f32_16x16x32_bf16 v[18:21], v[84:87], v[116:119], v[18:21]
	v_mfma_f32_16x16x32_bf16 v[10:13], v[92:95], v[116:119], v[10:13]
	v_mfma_f32_16x16x32_bf16 v[6:9], v[84:87], v[124:127], v[6:9]
	v_mfma_f32_16x16x32_bf16 v[2:5], v[92:95], v[124:127], v[2:5]
	v_mfma_f32_16x16x32_bf16 v[42:45], v[88:91], v[104:107], v[42:45]
	v_mfma_f32_16x16x32_bf16 v[38:41], v[96:99], v[104:107], v[38:41]
	v_mfma_f32_16x16x32_bf16 v[26:29], v[88:91], v[112:115], v[26:29]
	v_mfma_f32_16x16x32_bf16 v[22:25], v[96:99], v[112:115], v[22:25]
	v_mfma_f32_16x16x32_bf16 v[18:21], v[88:91], v[120:123], v[18:21]
	v_mfma_f32_16x16x32_bf16 v[10:13], v[96:99], v[120:123], v[10:13]
	v_mfma_f32_16x16x32_bf16 v[6:9], v[88:91], v[128:131], v[6:9]
	v_mfma_f32_16x16x32_bf16 v[2:5], v[96:99], v[128:131], v[2:5]
	s_barrier
	s_add_i32 s45, s45, 2
	s_add_u32 s10, s10, 0x100
	s_addc_u32 s11, s11, 0
	s_cmp_gt_u32 s45, 61
	s_cbranch_scc0 .LBB0_1300
	s_cmpk_lt_u32 s22, 0x100
	s_cbranch_scc0 .LBB0_1303
	s_barrier

.LBB0_1321:
	s_add_u32 s36, s2, 0xfffc0080
	s_addc_u32 s37, s3, -1
	s_add_i32 s40, 0, 0x10000
	s_cmp_eq_u32 s34, 4
	s_cselect_b32 s39, s29, s37
	s_cselect_b32 s38, s28, s36
	v_add_u32_e32 v0, s40, v141
	s_cselect_b32 s37, s5, s27
	s_cselect_b32 s36, s7, s25
	s_add_i32 s58, 0, 0x14000
	ds_read_b128 v[148:151], v0
	ds_read_b128 v[152:155], v0 offset:1024
	ds_read_b128 v[156:159], v0 offset:2048
	ds_read_b128 v[160:163], v0 offset:3072
	v_add_u32_e32 v0, s58, v141
	ds_read_b128 v[164:167], v0
	ds_read_b128 v[168:171], v0 offset:1024
	ds_read_b128 v[172:175], v0 offset:2048
	ds_read_b128 v[176:179], v0 offset:3072
	s_add_i32 m0, s49, 0xc000
	ds_read_b128 v[180:183], v186
	ds_read_b128 v[188:191], v186 offset:1024
	ds_read_b128 v[192:195], v186 offset:2048
	ds_read_b128 v[204:207], v186 offset:3072
	ds_read_b128 v[208:211], v186 offset:4096
	ds_read_b128 v[212:215], v186 offset:5120
	ds_read_b128 v[216:219], v186 offset:6144
	ds_read_b128 v[220:223], v186 offset:7168
	global_load_lds_dwordx4 v146, s[2:3]
	s_add_i32 m0, s49, 0xe000
	s_nop 0
	global_load_lds_dwordx4 v144, s[2:3]
	s_waitcnt vmcnt(8)
	s_waitcnt lgkmcnt(0)
	s_barrier
	s_waitcnt lgkmcnt(0)
	v_mfma_f32_16x16x32_bf16 v[130:133], v[148:151], v[180:183], v[130:133]
	v_mfma_f32_16x16x32_bf16 v[126:129], v[156:159], v[180:183], v[126:129]
	v_mfma_f32_16x16x32_bf16 v[114:117], v[148:151], v[192:195], v[114:117]
	v_mfma_f32_16x16x32_bf16 v[110:113], v[156:159], v[192:195], v[110:113]
	v_mfma_f32_16x16x32_bf16 v[98:101], v[148:151], v[208:211], v[98:101]
	v_mfma_f32_16x16x32_bf16 v[94:97], v[156:159], v[208:211], v[94:97]
	v_mfma_f32_16x16x32_bf16 v[82:85], v[148:151], v[216:219], v[82:85]
	v_mfma_f32_16x16x32_bf16 v[78:81], v[156:159], v[216:219], v[78:81]
	v_mfma_f32_16x16x32_bf16 v[130:133], v[152:155], v[188:191], v[130:133]
	v_mfma_f32_16x16x32_bf16 v[126:129], v[160:163], v[188:191], v[126:129]
	v_mfma_f32_16x16x32_bf16 v[114:117], v[152:155], v[204:207], v[114:117]
	v_mfma_f32_16x16x32_bf16 v[110:113], v[160:163], v[204:207], v[110:113]
	v_mfma_f32_16x16x32_bf16 v[98:101], v[152:155], v[212:215], v[98:101]
	v_mfma_f32_16x16x32_bf16 v[94:97], v[160:163], v[212:215], v[94:97]
	v_mfma_f32_16x16x32_bf16 v[82:85], v[152:155], v[220:223], v[82:85]
	v_mfma_f32_16x16x32_bf16 v[78:81], v[160:163], v[220:223], v[78:81]
	v_mfma_f32_16x16x32_bf16 v[122:125], v[164:167], v[180:183], v[122:125]
	v_mfma_f32_16x16x32_bf16 v[118:121], v[172:175], v[180:183], v[118:121]
	v_mfma_f32_16x16x32_bf16 v[106:109], v[164:167], v[192:195], v[106:109]
	v_mfma_f32_16x16x32_bf16 v[102:105], v[172:175], v[192:195], v[102:105]
	v_mfma_f32_16x16x32_bf16 v[90:93], v[164:167], v[208:211], v[90:93]
	v_mfma_f32_16x16x32_bf16 v[86:89], v[172:175], v[208:211], v[86:89]
	v_mfma_f32_16x16x32_bf16 v[74:77], v[164:167], v[216:219], v[74:77]
	v_mfma_f32_16x16x32_bf16 v[70:73], v[172:175], v[216:219], v[70:73]
	v_mfma_f32_16x16x32_bf16 v[122:125], v[168:171], v[188:191], v[122:125]
	v_mfma_f32_16x16x32_bf16 v[118:121], v[176:179], v[188:191], v[118:121]
	v_mfma_f32_16x16x32_bf16 v[106:109], v[168:171], v[204:207], v[106:109]
	v_mfma_f32_16x16x32_bf16 v[102:105], v[176:179], v[204:207], v[102:105]
	v_mfma_f32_16x16x32_bf16 v[90:93], v[168:171], v[212:215], v[90:93]
	v_mfma_f32_16x16x32_bf16 v[86:89], v[176:179], v[212:215], v[86:89]
	v_mfma_f32_16x16x32_bf16 v[74:77], v[168:171], v[220:223], v[74:77]
	v_mfma_f32_16x16x32_bf16 v[70:73], v[176:179], v[220:223], v[70:73]
	s_barrier
	s_add_i32 s40, s40, s48
	s_mov_b32 m0, s40
	ds_read_b128 v[180:183], v186 offset:16384
	ds_read_b128 v[188:191], v186 offset:17408
	ds_read_b128 v[192:195], v186 offset:18432
	ds_read_b128 v[204:207], v186 offset:19456
	ds_read_b128 v[208:211], v186 offset:20480
	ds_read_b128 v[212:215], v186 offset:21504
	ds_read_b128 v[216:219], v186 offset:22528
	ds_read_b128 v[220:223], v186 offset:23552
	global_load_lds_dwordx4 v134, s[36:37]
	s_add_i32 m0, s40, 0x2000
	s_add_u32 s56, s36, 0x20000
	s_addc_u32 s57, s37, 0
	s_add_i32 s40, s58, s48
	global_load_lds_dwordx4 v138, s[36:37]
	s_mov_b32 m0, s40
	s_add_u32 s90, s38, s96
	s_addc_u32 s91, s39, s97
	global_load_lds_dwordx4 v134, s[56:57]
	s_add_i32 m0, s40, 0x2000
	s_nop 0
	global_load_lds_dwordx4 v138, s[56:57]
	s_mov_b32 m0, s49
	s_nop 0
	global_load_lds_dwordx4 v14, s[38:39]
	s_mov_b32 m0, s50
	s_nop 0
	global_load_lds_dwordx4 v136, s[38:39]
	s_waitcnt vmcnt(8)
	s_waitcnt lgkmcnt(0)
	s_barrier
	s_waitcnt lgkmcnt(0)
	v_mfma_f32_16x16x32_bf16 v[66:69], v[148:151], v[180:183], v[66:69]
	v_mfma_f32_16x16x32_bf16 v[62:65], v[156:159], v[180:183], v[62:65]
	v_mfma_f32_16x16x32_bf16 v[50:53], v[148:151], v[192:195], v[50:53]
	v_mfma_f32_16x16x32_bf16 v[46:49], v[156:159], v[192:195], v[46:49]
	v_mfma_f32_16x16x32_bf16 v[34:37], v[148:151], v[208:211], v[34:37]
	v_mfma_f32_16x16x32_bf16 v[30:33], v[156:159], v[208:211], v[30:33]
	v_mfma_f32_16x16x32_bf16 v[18:21], v[148:151], v[216:219], v[18:21]
	v_mfma_f32_16x16x32_bf16 v[10:13], v[156:159], v[216:219], v[10:13]
	v_mfma_f32_16x16x32_bf16 v[66:69], v[152:155], v[188:191], v[66:69]
	v_mfma_f32_16x16x32_bf16 v[62:65], v[160:163], v[188:191], v[62:65]
	v_mfma_f32_16x16x32_bf16 v[50:53], v[152:155], v[204:207], v[50:53]
	v_mfma_f32_16x16x32_bf16 v[46:49], v[160:163], v[204:207], v[46:49]
	v_mfma_f32_16x16x32_bf16 v[34:37], v[152:155], v[212:215], v[34:37]
	v_mfma_f32_16x16x32_bf16 v[30:33], v[160:163], v[212:215], v[30:33]
	v_mfma_f32_16x16x32_bf16 v[18:21], v[152:155], v[220:223], v[18:21]
	v_mfma_f32_16x16x32_bf16 v[10:13], v[160:163], v[220:223], v[10:13]
	v_mfma_f32_16x16x32_bf16 v[58:61], v[164:167], v[180:183], v[58:61]
	v_mfma_f32_16x16x32_bf16 v[54:57], v[172:175], v[180:183], v[54:57]
	v_mfma_f32_16x16x32_bf16 v[42:45], v[164:167], v[192:195], v[42:45]
	v_mfma_f32_16x16x32_bf16 v[38:41], v[172:175], v[192:195], v[38:41]
	v_mfma_f32_16x16x32_bf16 v[26:29], v[164:167], v[208:211], v[26:29]
	v_mfma_f32_16x16x32_bf16 v[22:25], v[172:175], v[208:211], v[22:25]
	v_mfma_f32_16x16x32_bf16 v[6:9], v[164:167], v[216:219], v[6:9]
	v_mfma_f32_16x16x32_bf16 v[2:5], v[172:175], v[216:219], v[2:5]
	v_mfma_f32_16x16x32_bf16 v[58:61], v[168:171], v[188:191], v[58:61]
	v_mfma_f32_16x16x32_bf16 v[54:57], v[176:179], v[188:191], v[54:57]
	v_mfma_f32_16x16x32_bf16 v[42:45], v[168:171], v[204:207], v[42:45]
	v_mfma_f32_16x16x32_bf16 v[38:41], v[176:179], v[204:207], v[38:41]
	v_mfma_f32_16x16x32_bf16 v[26:29], v[168:171], v[212:215], v[26:29]
	v_mfma_f32_16x16x32_bf16 v[22:25], v[176:179], v[212:215], v[22:25]
	v_mfma_f32_16x16x32_bf16 v[6:9], v[168:171], v[220:223], v[6:9]
	v_mfma_f32_16x16x32_bf16 v[2:5], v[176:179], v[220:223], v[2:5]
	s_barrier
	s_add_i32 s40, 0, 0x18000
	v_add_u32_e32 v0, s40, v141
	s_add_i32 s56, 0, 0x1c000
	ds_read_b128 v[148:151], v0
	ds_read_b128 v[152:155], v0 offset:1024
	ds_read_b128 v[156:159], v0 offset:2048
	ds_read_b128 v[160:163], v0 offset:3072
	v_add_u32_e32 v0, s56, v141
	ds_read_b128 v[164:167], v0
	ds_read_b128 v[168:171], v0 offset:1024
	ds_read_b128 v[172:175], v0 offset:2048
	ds_read_b128 v[176:179], v0 offset:3072
	s_add_u32 s38, s38, 0x40000
	s_addc_u32 s39, s39, 0
	s_mov_b32 m0, s51
	ds_read_b128 v[180:183], v186 offset:32768
	ds_read_b128 v[188:191], v186 offset:33792
	ds_read_b128 v[192:195], v186 offset:34816
	ds_read_b128 v[204:207], v186 offset:35840
	ds_read_b128 v[208:211], v186 offset:36864
	ds_read_b128 v[212:215], v186 offset:37888
	ds_read_b128 v[216:219], v186 offset:38912
	ds_read_b128 v[220:223], v186 offset:39936
	global_load_lds_dwordx4 v14, s[38:39]
	s_mov_b32 m0, s52
	s_nop 0
	global_load_lds_dwordx4 v136, s[38:39]
	s_waitcnt vmcnt(8)
	s_waitcnt lgkmcnt(0)
	s_barrier
	s_waitcnt lgkmcnt(0)
	v_mfma_f32_16x16x32_bf16 v[130:133], v[148:151], v[180:183], v[130:133]
	v_mfma_f32_16x16x32_bf16 v[126:129], v[156:159], v[180:183], v[126:129]
	v_mfma_f32_16x16x32_bf16 v[114:117], v[148:151], v[192:195], v[114:117]
	v_mfma_f32_16x16x32_bf16 v[110:113], v[156:159], v[192:195], v[110:113]
	v_mfma_f32_16x16x32_bf16 v[98:101], v[148:151], v[208:211], v[98:101]
	v_mfma_f32_16x16x32_bf16 v[94:97], v[156:159], v[208:211], v[94:97]
	v_mfma_f32_16x16x32_bf16 v[82:85], v[148:151], v[216:219], v[82:85]
	v_mfma_f32_16x16x32_bf16 v[78:81], v[156:159], v[216:219], v[78:81]
	v_mfma_f32_16x16x32_bf16 v[130:133], v[152:155], v[188:191], v[130:133]
	v_mfma_f32_16x16x32_bf16 v[126:129], v[160:163], v[188:191], v[126:129]
	v_mfma_f32_16x16x32_bf16 v[114:117], v[152:155], v[204:207], v[114:117]
	v_mfma_f32_16x16x32_bf16 v[110:113], v[160:163], v[204:207], v[110:113]
	v_mfma_f32_16x16x32_bf16 v[98:101], v[152:155], v[212:215], v[98:101]
	v_mfma_f32_16x16x32_bf16 v[94:97], v[160:163], v[212:215], v[94:97]
	v_mfma_f32_16x16x32_bf16 v[82:85], v[152:155], v[220:223], v[82:85]
	v_mfma_f32_16x16x32_bf16 v[78:81], v[160:163], v[220:223], v[78:81]
	v_mfma_f32_16x16x32_bf16 v[122:125], v[164:167], v[180:183], v[122:125]
	v_mfma_f32_16x16x32_bf16 v[118:121], v[172:175], v[180:183], v[118:121]
	v_mfma_f32_16x16x32_bf16 v[106:109], v[164:167], v[192:195], v[106:109]
	v_mfma_f32_16x16x32_bf16 v[102:105], v[172:175], v[192:195], v[102:105]
	v_mfma_f32_16x16x32_bf16 v[90:93], v[164:167], v[208:211], v[90:93]
	v_mfma_f32_16x16x32_bf16 v[86:89], v[172:175], v[208:211], v[86:89]
	v_mfma_f32_16x16x32_bf16 v[74:77], v[164:167], v[216:219], v[74:77]
	v_mfma_f32_16x16x32_bf16 v[70:73], v[172:175], v[216:219], v[70:73]
	v_mfma_f32_16x16x32_bf16 v[122:125], v[168:171], v[188:191], v[122:125]
	v_mfma_f32_16x16x32_bf16 v[118:121], v[176:179], v[188:191], v[118:121]
	v_mfma_f32_16x16x32_bf16 v[106:109], v[168:171], v[204:207], v[106:109]
	v_mfma_f32_16x16x32_bf16 v[102:105], v[176:179], v[204:207], v[102:105]
	v_mfma_f32_16x16x32_bf16 v[90:93], v[168:171], v[212:215], v[90:93]
	v_mfma_f32_16x16x32_bf16 v[86:89], v[176:179], v[212:215], v[86:89]
	v_mfma_f32_16x16x32_bf16 v[74:77], v[168:171], v[220:223], v[74:77]
	v_mfma_f32_16x16x32_bf16 v[70:73], v[176:179], v[220:223], v[70:73]
	s_barrier
	s_add_i32 s38, s40, s48
	s_add_u32 s88, s36, s96
	s_addc_u32 s89, s37, s97
	s_mov_b32 m0, s38
	ds_read_b128 v[180:183], v186 offset:49152
	ds_read_b128 v[188:191], v186 offset:50176
	ds_read_b128 v[192:195], v186 offset:51200
	ds_read_b128 v[204:207], v186 offset:52224
	ds_read_b128 v[208:211], v186 offset:53248
	ds_read_b128 v[212:215], v186 offset:54272
	ds_read_b128 v[216:219], v186 offset:55296
	ds_read_b128 v[220:223], v186 offset:56320
	global_load_lds_dwordx4 v134, s[88:89]
	s_add_i32 m0, s38, 0x2000
	s_add_u32 s36, s36, 0x20080
	s_addc_u32 s37, s37, 0
	s_add_i32 s38, s56, s48
	global_load_lds_dwordx4 v138, s[88:89]
	s_mov_b32 m0, s38
	s_nop 0
	global_load_lds_dwordx4 v134, s[36:37]
	s_add_i32 m0, s38, 0x2000
	s_nop 0
	global_load_lds_dwordx4 v138, s[36:37]
	s_mov_b32 m0, s53
	s_nop 0
	global_load_lds_dwordx4 v14, s[90:91]
	s_mov_b32 m0, s54
	s_nop 0
	global_load_lds_dwordx4 v136, s[90:91]
	s_waitcnt vmcnt(8)
	s_waitcnt lgkmcnt(0)
	s_barrier
	s_waitcnt lgkmcnt(0)
	v_mfma_f32_16x16x32_bf16 v[66:69], v[148:151], v[180:183], v[66:69]
	v_mfma_f32_16x16x32_bf16 v[62:65], v[156:159], v[180:183], v[62:65]
	v_mfma_f32_16x16x32_bf16 v[50:53], v[148:151], v[192:195], v[50:53]
	v_mfma_f32_16x16x32_bf16 v[46:49], v[156:159], v[192:195], v[46:49]
	v_mfma_f32_16x16x32_bf16 v[34:37], v[148:151], v[208:211], v[34:37]
	v_mfma_f32_16x16x32_bf16 v[30:33], v[156:159], v[208:211], v[30:33]
	v_mfma_f32_16x16x32_bf16 v[18:21], v[148:151], v[216:219], v[18:21]
	v_mfma_f32_16x16x32_bf16 v[10:13], v[156:159], v[216:219], v[10:13]
	v_mfma_f32_16x16x32_bf16 v[66:69], v[152:155], v[188:191], v[66:69]
	v_mfma_f32_16x16x32_bf16 v[62:65], v[160:163], v[188:191], v[62:65]
	v_mfma_f32_16x16x32_bf16 v[50:53], v[152:155], v[204:207], v[50:53]
	v_mfma_f32_16x16x32_bf16 v[46:49], v[160:163], v[204:207], v[46:49]
	v_mfma_f32_16x16x32_bf16 v[34:37], v[152:155], v[212:215], v[34:37]
	v_mfma_f32_16x16x32_bf16 v[30:33], v[160:163], v[212:215], v[30:33]
	v_mfma_f32_16x16x32_bf16 v[18:21], v[152:155], v[220:223], v[18:21]
	v_mfma_f32_16x16x32_bf16 v[10:13], v[160:163], v[220:223], v[10:13]
	v_mfma_f32_16x16x32_bf16 v[58:61], v[164:167], v[180:183], v[58:61]
	v_mfma_f32_16x16x32_bf16 v[54:57], v[172:175], v[180:183], v[54:57]
	v_mfma_f32_16x16x32_bf16 v[42:45], v[164:167], v[192:195], v[42:45]
	v_mfma_f32_16x16x32_bf16 v[38:41], v[172:175], v[192:195], v[38:41]
	v_mfma_f32_16x16x32_bf16 v[26:29], v[164:167], v[208:211], v[26:29]
	v_mfma_f32_16x16x32_bf16 v[22:25], v[172:175], v[208:211], v[22:25]
	v_mfma_f32_16x16x32_bf16 v[6:9], v[164:167], v[216:219], v[6:9]
	v_mfma_f32_16x16x32_bf16 v[2:5], v[172:175], v[216:219], v[2:5]
	v_mfma_f32_16x16x32_bf16 v[58:61], v[168:171], v[188:191], v[58:61]
	v_mfma_f32_16x16x32_bf16 v[54:57], v[176:179], v[188:191], v[54:57]
	v_mfma_f32_16x16x32_bf16 v[42:45], v[168:171], v[204:207], v[42:45]
	v_mfma_f32_16x16x32_bf16 v[38:41], v[176:179], v[204:207], v[38:41]
	v_mfma_f32_16x16x32_bf16 v[26:29], v[168:171], v[212:215], v[26:29]
	v_mfma_f32_16x16x32_bf16 v[22:25], v[176:179], v[212:215], v[22:25]
	v_mfma_f32_16x16x32_bf16 v[6:9], v[168:171], v[220:223], v[6:9]
	v_mfma_f32_16x16x32_bf16 v[2:5], v[176:179], v[220:223], v[2:5]
	s_barrier
	s_add_i32 s34, s34, 2
	s_add_u32 s25, s25, 0x100
	s_addc_u32 s27, s27, 0
	s_add_u32 s2, s2, 0x100
	s_addc_u32 s3, s3, 0
	s_cmp_gt_u32 s34, 5
	s_cbranch_scc0 .LBB0_1321
	s_and_b64 vcc, exec, s[22:23]
	s_cbranch_vccz .LBB0_1324
	s_barrier

.LBB0_2399:
	s_add_u32 s90, s22, s40
	s_addc_u32 s91, s23, s41
	s_add_u32 s90, s90, 0x80080
	s_addc_u32 s91, s91, 0
	s_add_u32 s44, s22, s40
	s_addc_u32 s45, s23, s41
	s_add_u32 s44, s44, 0x100
	s_addc_u32 s45, s45, 0
	s_add_u32 s67, s63, s40
	s_addc_u32 s68, s64, s41
	s_add_i32 s69, 0, 0x10000
	s_cmpk_eq_i32 s40, 0xf00
	s_cselect_b32 s47, s25, s45
	s_cselect_b32 s46, s34, s44
	s_cselect_b32 s45, s27, s68
	s_cselect_b32 s44, s65, s67
	s_add_i32 s67, 0, 0x14000
	v_add_u32_e32 v154, s69, v180
	v_add_u32_e32 v170, s67, v180
	ds_read_b128 v[142:145], v154
	ds_read_b128 v[146:149], v154 offset:1024
	ds_read_b128 v[150:153], v154 offset:2048
	ds_read_b128 v[154:157], v154 offset:3072
	ds_read_b128 v[158:161], v170
	ds_read_b128 v[162:165], v170 offset:1024
	ds_read_b128 v[166:169], v170 offset:2048
	ds_read_b128 v[170:173], v170 offset:3072
	s_add_i32 m0, s5, 0xc000
	ds_read_b128 v[174:177], v184
	ds_read_b128 v[186:189], v184 offset:1024
	ds_read_b128 v[190:193], v184 offset:2048
	ds_read_b128 v[194:197], v184 offset:3072
	ds_read_b128 v[200:203], v184 offset:4096
	ds_read_b128 v[204:207], v184 offset:5120
	ds_read_b128 v[208:211], v184 offset:6144
	ds_read_b128 v[212:215], v184 offset:7168
	global_load_lds_dwordx4 v136, s[90:91]
	s_add_i32 m0, s5, 0xe000
	s_nop 0
	global_load_lds_dwordx4 v134, s[90:91]
	s_waitcnt vmcnt(8)
	s_waitcnt lgkmcnt(0)
	s_barrier
	s_waitcnt lgkmcnt(0)
	v_mfma_f32_16x16x32_bf16 v[130:133], v[142:145], v[174:177], v[130:133]
	v_mfma_f32_16x16x32_bf16 v[126:129], v[150:153], v[174:177], v[126:129]
	v_mfma_f32_16x16x32_bf16 v[122:125], v[142:145], v[190:193], v[122:125]
	v_mfma_f32_16x16x32_bf16 v[118:121], v[150:153], v[190:193], v[118:121]
	v_mfma_f32_16x16x32_bf16 v[114:117], v[142:145], v[200:203], v[114:117]
	v_mfma_f32_16x16x32_bf16 v[110:113], v[150:153], v[200:203], v[110:113]
	v_mfma_f32_16x16x32_bf16 v[106:109], v[142:145], v[208:211], v[106:109]
	v_mfma_f32_16x16x32_bf16 v[102:105], v[150:153], v[208:211], v[102:105]
	v_mfma_f32_16x16x32_bf16 v[130:133], v[146:149], v[186:189], v[130:133]
	v_mfma_f32_16x16x32_bf16 v[126:129], v[154:157], v[186:189], v[126:129]
	v_mfma_f32_16x16x32_bf16 v[122:125], v[146:149], v[194:197], v[122:125]
	v_mfma_f32_16x16x32_bf16 v[118:121], v[154:157], v[194:197], v[118:121]
	v_mfma_f32_16x16x32_bf16 v[114:117], v[146:149], v[204:207], v[114:117]
	v_mfma_f32_16x16x32_bf16 v[110:113], v[154:157], v[204:207], v[110:113]
	v_mfma_f32_16x16x32_bf16 v[106:109], v[146:149], v[212:215], v[106:109]
	v_mfma_f32_16x16x32_bf16 v[102:105], v[154:157], v[212:215], v[102:105]
	v_mfma_f32_16x16x32_bf16 v[98:101], v[158:161], v[174:177], v[98:101]
	v_mfma_f32_16x16x32_bf16 v[94:97], v[166:169], v[174:177], v[94:97]
	v_mfma_f32_16x16x32_bf16 v[90:93], v[158:161], v[190:193], v[90:93]
	v_mfma_f32_16x16x32_bf16 v[86:89], v[166:169], v[190:193], v[86:89]
	v_mfma_f32_16x16x32_bf16 v[82:85], v[158:161], v[200:203], v[82:85]
	v_mfma_f32_16x16x32_bf16 v[78:81], v[166:169], v[200:203], v[78:81]
	v_mfma_f32_16x16x32_bf16 v[74:77], v[158:161], v[208:211], v[74:77]
	v_mfma_f32_16x16x32_bf16 v[70:73], v[166:169], v[208:211], v[70:73]
	v_mfma_f32_16x16x32_bf16 v[98:101], v[162:165], v[186:189], v[98:101]
	v_mfma_f32_16x16x32_bf16 v[94:97], v[170:173], v[186:189], v[94:97]
	v_mfma_f32_16x16x32_bf16 v[90:93], v[162:165], v[194:197], v[90:93]
	v_mfma_f32_16x16x32_bf16 v[86:89], v[170:173], v[194:197], v[86:89]
	v_mfma_f32_16x16x32_bf16 v[82:85], v[162:165], v[204:207], v[82:85]
	v_mfma_f32_16x16x32_bf16 v[78:81], v[170:173], v[204:207], v[78:81]
	v_mfma_f32_16x16x32_bf16 v[74:77], v[162:165], v[212:215], v[74:77]
	v_mfma_f32_16x16x32_bf16 v[70:73], v[170:173], v[212:215], v[70:73]
	s_barrier
	s_add_i32 s68, s69, s53
	s_mov_b32 m0, s68
	ds_read_b128 v[174:177], v184 offset:16384
	ds_read_b128 v[186:189], v184 offset:17408
	ds_read_b128 v[190:193], v184 offset:18432
	ds_read_b128 v[194:197], v184 offset:19456
	ds_read_b128 v[200:203], v184 offset:20480
	ds_read_b128 v[204:207], v184 offset:21504
	ds_read_b128 v[208:211], v184 offset:22528
	ds_read_b128 v[212:215], v184 offset:23552
	global_load_lds_dwordx4 v0, s[44:45]
	s_add_i32 m0, s68, 0x2000
	s_add_u32 s68, s44, 0x80000
	s_addc_u32 s69, s45, 0
	s_add_i32 s67, s67, s53
	global_load_lds_dwordx4 v14, s[44:45]
	s_mov_b32 m0, s67
	s_add_u32 s92, s46, s96
	s_addc_u32 s93, s47, s97
	global_load_lds_dwordx4 v0, s[68:69]
	s_add_i32 m0, s67, 0x2000
	s_nop 0
	global_load_lds_dwordx4 v14, s[68:69]
	s_mov_b32 m0, s5
	s_nop 0
	global_load_lds_dwordx4 v0, s[46:47]
	s_mov_b32 m0, s7
	s_nop 0
	global_load_lds_dwordx4 v14, s[46:47]
	s_waitcnt vmcnt(8)
	s_waitcnt lgkmcnt(0)
	s_barrier
	s_waitcnt lgkmcnt(0)
	v_mfma_f32_16x16x32_bf16 v[66:69], v[142:145], v[174:177], v[66:69]
	v_mfma_f32_16x16x32_bf16 v[62:65], v[150:153], v[174:177], v[62:65]
	v_mfma_f32_16x16x32_bf16 v[58:61], v[142:145], v[190:193], v[58:61]
	v_mfma_f32_16x16x32_bf16 v[54:57], v[150:153], v[190:193], v[54:57]
	v_mfma_f32_16x16x32_bf16 v[50:53], v[142:145], v[200:203], v[50:53]
	v_mfma_f32_16x16x32_bf16 v[46:49], v[150:153], v[200:203], v[46:49]
	v_mfma_f32_16x16x32_bf16 v[42:45], v[142:145], v[208:211], v[42:45]
	v_mfma_f32_16x16x32_bf16 v[38:41], v[150:153], v[208:211], v[38:41]
	v_mfma_f32_16x16x32_bf16 v[66:69], v[146:149], v[186:189], v[66:69]
	v_mfma_f32_16x16x32_bf16 v[62:65], v[154:157], v[186:189], v[62:65]
	v_mfma_f32_16x16x32_bf16 v[58:61], v[146:149], v[194:197], v[58:61]
	v_mfma_f32_16x16x32_bf16 v[54:57], v[154:157], v[194:197], v[54:57]
	v_mfma_f32_16x16x32_bf16 v[50:53], v[146:149], v[204:207], v[50:53]
	v_mfma_f32_16x16x32_bf16 v[46:49], v[154:157], v[204:207], v[46:49]
	v_mfma_f32_16x16x32_bf16 v[42:45], v[146:149], v[212:215], v[42:45]
	v_mfma_f32_16x16x32_bf16 v[38:41], v[154:157], v[212:215], v[38:41]
	v_mfma_f32_16x16x32_bf16 v[34:37], v[158:161], v[174:177], v[34:37]
	v_mfma_f32_16x16x32_bf16 v[30:33], v[166:169], v[174:177], v[30:33]
	v_mfma_f32_16x16x32_bf16 v[26:29], v[158:161], v[190:193], v[26:29]
	v_mfma_f32_16x16x32_bf16 v[22:25], v[166:169], v[190:193], v[22:25]
	v_mfma_f32_16x16x32_bf16 v[18:21], v[158:161], v[200:203], v[18:21]
	v_mfma_f32_16x16x32_bf16 v[10:13], v[166:169], v[200:203], v[10:13]
	v_mfma_f32_16x16x32_bf16 v[6:9], v[158:161], v[208:211], v[6:9]
	v_mfma_f32_16x16x32_bf16 v[2:5], v[166:169], v[208:211], v[2:5]
	v_mfma_f32_16x16x32_bf16 v[34:37], v[162:165], v[186:189], v[34:37]
	v_mfma_f32_16x16x32_bf16 v[30:33], v[170:173], v[186:189], v[30:33]
	v_mfma_f32_16x16x32_bf16 v[26:29], v[162:165], v[194:197], v[26:29]
	v_mfma_f32_16x16x32_bf16 v[22:25], v[170:173], v[194:197], v[22:25]
	v_mfma_f32_16x16x32_bf16 v[18:21], v[162:165], v[204:207], v[18:21]
	v_mfma_f32_16x16x32_bf16 v[10:13], v[170:173], v[204:207], v[10:13]
	v_mfma_f32_16x16x32_bf16 v[6:9], v[162:165], v[212:215], v[6:9]
	v_mfma_f32_16x16x32_bf16 v[2:5], v[170:173], v[212:215], v[2:5]
	s_barrier
	s_add_i32 s67, 0, 0x18000
	s_add_i32 s68, 0, 0x1c000
	v_add_u32_e32 v154, s67, v180
	v_add_u32_e32 v170, s68, v180
	ds_read_b128 v[142:145], v154
	ds_read_b128 v[146:149], v154 offset:1024
	ds_read_b128 v[150:153], v154 offset:2048
	ds_read_b128 v[154:157], v154 offset:3072
	ds_read_b128 v[158:161], v170
	ds_read_b128 v[162:165], v170 offset:1024
	ds_read_b128 v[166:169], v170 offset:2048
	ds_read_b128 v[170:173], v170 offset:3072
	s_add_u32 s46, s46, 0x80000
	s_addc_u32 s47, s47, 0
	s_mov_b32 m0, s54
	ds_read_b128 v[174:177], v184 offset:32768
	ds_read_b128 v[186:189], v184 offset:33792
	ds_read_b128 v[190:193], v184 offset:34816
	ds_read_b128 v[194:197], v184 offset:35840
	ds_read_b128 v[200:203], v184 offset:36864
	ds_read_b128 v[204:207], v184 offset:37888
	ds_read_b128 v[208:211], v184 offset:38912
	ds_read_b128 v[212:215], v184 offset:39936
	global_load_lds_dwordx4 v0, s[46:47]
	s_mov_b32 m0, s55
	s_nop 0
	global_load_lds_dwordx4 v14, s[46:47]
	s_waitcnt vmcnt(8)
	s_waitcnt lgkmcnt(0)
	s_barrier
	s_waitcnt lgkmcnt(0)
	v_mfma_f32_16x16x32_bf16 v[130:133], v[142:145], v[174:177], v[130:133]
	v_mfma_f32_16x16x32_bf16 v[126:129], v[150:153], v[174:177], v[126:129]
	v_mfma_f32_16x16x32_bf16 v[122:125], v[142:145], v[190:193], v[122:125]
	v_mfma_f32_16x16x32_bf16 v[118:121], v[150:153], v[190:193], v[118:121]
	v_mfma_f32_16x16x32_bf16 v[114:117], v[142:145], v[200:203], v[114:117]
	v_mfma_f32_16x16x32_bf16 v[110:113], v[150:153], v[200:203], v[110:113]
	v_mfma_f32_16x16x32_bf16 v[106:109], v[142:145], v[208:211], v[106:109]
	v_mfma_f32_16x16x32_bf16 v[102:105], v[150:153], v[208:211], v[102:105]
	v_mfma_f32_16x16x32_bf16 v[130:133], v[146:149], v[186:189], v[130:133]
	v_mfma_f32_16x16x32_bf16 v[126:129], v[154:157], v[186:189], v[126:129]
	v_mfma_f32_16x16x32_bf16 v[122:125], v[146:149], v[194:197], v[122:125]
	v_mfma_f32_16x16x32_bf16 v[118:121], v[154:157], v[194:197], v[118:121]
	v_mfma_f32_16x16x32_bf16 v[114:117], v[146:149], v[204:207], v[114:117]
	v_mfma_f32_16x16x32_bf16 v[110:113], v[154:157], v[204:207], v[110:113]
	v_mfma_f32_16x16x32_bf16 v[106:109], v[146:149], v[212:215], v[106:109]
	v_mfma_f32_16x16x32_bf16 v[102:105], v[154:157], v[212:215], v[102:105]
	v_mfma_f32_16x16x32_bf16 v[98:101], v[158:161], v[174:177], v[98:101]
	v_mfma_f32_16x16x32_bf16 v[94:97], v[166:169], v[174:177], v[94:97]
	v_mfma_f32_16x16x32_bf16 v[90:93], v[158:161], v[190:193], v[90:93]
	v_mfma_f32_16x16x32_bf16 v[86:89], v[166:169], v[190:193], v[86:89]
	v_mfma_f32_16x16x32_bf16 v[82:85], v[158:161], v[200:203], v[82:85]
	v_mfma_f32_16x16x32_bf16 v[78:81], v[166:169], v[200:203], v[78:81]
	v_mfma_f32_16x16x32_bf16 v[74:77], v[158:161], v[208:211], v[74:77]
	v_mfma_f32_16x16x32_bf16 v[70:73], v[166:169], v[208:211], v[70:73]
	v_mfma_f32_16x16x32_bf16 v[98:101], v[162:165], v[186:189], v[98:101]
	v_mfma_f32_16x16x32_bf16 v[94:97], v[170:173], v[186:189], v[94:97]
	v_mfma_f32_16x16x32_bf16 v[90:93], v[162:165], v[194:197], v[90:93]
	v_mfma_f32_16x16x32_bf16 v[86:89], v[170:173], v[194:197], v[86:89]
	v_mfma_f32_16x16x32_bf16 v[82:85], v[162:165], v[204:207], v[82:85]
	v_mfma_f32_16x16x32_bf16 v[78:81], v[170:173], v[204:207], v[78:81]
	v_mfma_f32_16x16x32_bf16 v[74:77], v[162:165], v[212:215], v[74:77]
	v_mfma_f32_16x16x32_bf16 v[70:73], v[170:173], v[212:215], v[70:73]
	s_barrier
	s_add_i32 s46, s67, s53
	s_add_u32 s90, s44, s96
	s_addc_u32 s91, s45, s97
	s_mov_b32 m0, s46
	ds_read_b128 v[174:177], v184 offset:49152
	ds_read_b128 v[186:189], v184 offset:50176
	ds_read_b128 v[190:193], v184 offset:51200
	ds_read_b128 v[194:197], v184 offset:52224
	ds_read_b128 v[200:203], v184 offset:53248
	ds_read_b128 v[204:207], v184 offset:54272
	ds_read_b128 v[208:211], v184 offset:55296
	ds_read_b128 v[212:215], v184 offset:56320
	global_load_lds_dwordx4 v0, s[90:91]
	s_add_i32 m0, s46, 0x2000
	s_add_u32 s44, s44, 0x80080
	s_addc_u32 s45, s45, 0
	s_add_i32 s46, s68, s53
	global_load_lds_dwordx4 v14, s[90:91]
	s_mov_b32 m0, s46
	s_nop 0
	global_load_lds_dwordx4 v0, s[44:45]
	s_add_i32 m0, s46, 0x2000
	s_nop 0
	global_load_lds_dwordx4 v14, s[44:45]
	s_mov_b32 m0, s59
	s_nop 0
	global_load_lds_dwordx4 v0, s[92:93]
	s_mov_b32 m0, s60
	s_nop 0
	global_load_lds_dwordx4 v14, s[92:93]
	s_waitcnt vmcnt(8)
	s_waitcnt lgkmcnt(0)
	s_barrier
	s_waitcnt lgkmcnt(0)
	v_mfma_f32_16x16x32_bf16 v[66:69], v[142:145], v[174:177], v[66:69]
	v_mfma_f32_16x16x32_bf16 v[62:65], v[150:153], v[174:177], v[62:65]
	v_mfma_f32_16x16x32_bf16 v[58:61], v[142:145], v[190:193], v[58:61]
	v_mfma_f32_16x16x32_bf16 v[54:57], v[150:153], v[190:193], v[54:57]
	v_mfma_f32_16x16x32_bf16 v[50:53], v[142:145], v[200:203], v[50:53]
	v_mfma_f32_16x16x32_bf16 v[46:49], v[150:153], v[200:203], v[46:49]
	v_mfma_f32_16x16x32_bf16 v[42:45], v[142:145], v[208:211], v[42:45]
	v_mfma_f32_16x16x32_bf16 v[38:41], v[150:153], v[208:211], v[38:41]
	v_mfma_f32_16x16x32_bf16 v[66:69], v[146:149], v[186:189], v[66:69]
	v_mfma_f32_16x16x32_bf16 v[62:65], v[154:157], v[186:189], v[62:65]
	v_mfma_f32_16x16x32_bf16 v[58:61], v[146:149], v[194:197], v[58:61]
	v_mfma_f32_16x16x32_bf16 v[54:57], v[154:157], v[194:197], v[54:57]
	v_mfma_f32_16x16x32_bf16 v[50:53], v[146:149], v[204:207], v[50:53]
	v_mfma_f32_16x16x32_bf16 v[46:49], v[154:157], v[204:207], v[46:49]
	v_mfma_f32_16x16x32_bf16 v[42:45], v[146:149], v[212:215], v[42:45]
	v_mfma_f32_16x16x32_bf16 v[38:41], v[154:157], v[212:215], v[38:41]
	v_mfma_f32_16x16x32_bf16 v[34:37], v[158:161], v[174:177], v[34:37]
	v_mfma_f32_16x16x32_bf16 v[30:33], v[166:169], v[174:177], v[30:33]
	v_mfma_f32_16x16x32_bf16 v[26:29], v[158:161], v[190:193], v[26:29]
	v_mfma_f32_16x16x32_bf16 v[22:25], v[166:169], v[190:193], v[22:25]
	v_mfma_f32_16x16x32_bf16 v[18:21], v[158:161], v[200:203], v[18:21]
	v_mfma_f32_16x16x32_bf16 v[10:13], v[166:169], v[200:203], v[10:13]
	v_mfma_f32_16x16x32_bf16 v[6:9], v[158:161], v[208:211], v[6:9]
	v_mfma_f32_16x16x32_bf16 v[2:5], v[166:169], v[208:211], v[2:5]
	v_mfma_f32_16x16x32_bf16 v[34:37], v[162:165], v[186:189], v[34:37]
	v_mfma_f32_16x16x32_bf16 v[30:33], v[170:173], v[186:189], v[30:33]
	v_mfma_f32_16x16x32_bf16 v[26:29], v[162:165], v[194:197], v[26:29]
	v_mfma_f32_16x16x32_bf16 v[22:25], v[170:173], v[194:197], v[22:25]
	v_mfma_f32_16x16x32_bf16 v[18:21], v[162:165], v[204:207], v[18:21]
	v_mfma_f32_16x16x32_bf16 v[10:13], v[170:173], v[204:207], v[10:13]
	v_mfma_f32_16x16x32_bf16 v[6:9], v[162:165], v[212:215], v[6:9]
	v_mfma_f32_16x16x32_bf16 v[2:5], v[170:173], v[212:215], v[2:5]
	s_barrier
	s_add_i32 s66, s66, 2
	s_add_u32 s40, s40, 0x100
	s_addc_u32 s41, s41, 0
	s_cmp_gt_u32 s66, 29
	s_cbranch_scc0 .LBB0_2399
	s_and_b64 vcc, exec, s[18:19]
	s_cbranch_vccz .LBB0_2402
	s_barrier
